# P0 transposer: skip the pacing sleep on each wave's first iteration (memory idle at that point); on top of v067
# speedup vs baseline: 1.0066x; 1.0066x over previous
; __device__ __forceinline__ void p0_prologue(const Ptrs& P, LAS unsigned char* lds, int vcu, int G, int tid) {
;     ...
;         for (int it = gw; it < NITEMS; it += NGW) {
;             const int nit = it + NGW; const bool has_n = nit < NITEMS;
;             f32x4 nv[8];
;             const TItem nxt = t_decode(P, has_n ? nit : it, lane); t_load(nxt, nv);
.LBB0_39:
	s_cmp_eq_u32 s50, s3
	s_cbranch_scc1 .Lp0_nosleep
	s_sleep 80
